# NA: trailer waves touch the K/V/Q lines needed two grid rows ahead (L2 prefetch by 3 dword loads per row); their top-of-row wait becomes vmcnt(3)
# baseline (speedup 1.0000x reference)
; __device__ __forceinline__ void ph_na_mfma(const Args& a, const Frame& F, int l) {
;     ...
;         for (int j = 0; j < m; ++j) {
;             const int r = r0 + j, rs = min(max(r - 4, 0), R - 8);
;             pg8::bf16x8 qf0 = qn0, qf1 = qn1;
;             asm volatile("" : "+v"(qf0), "+v"(qf1) :: "memory");
;             if (half == 1 && j > 0) { *(v2u*)(stp) = st0; *(v2u*)(stp + 16) = st1; *(v2u*)(stp + 32) = st2; *(v2u*)(stp + 48) = st3; }
.LBB0_359:
	s_cmp_lg_u64 s[44:45], 0
	s_cbranch_scc1 .Lna_tr_wait
	s_waitcnt vmcnt(0)
	s_branch .Lna_wait_done
.Lna_tr_wait:
	s_waitcnt vmcnt(3)
.Lna_wait_done:
	v_mov_b64_e32 v[48:49], v[4:5]
	v_mov_b64_e32 v[44:45], v[8:9]
	v_mov_b64_e32 v[46:47], v[2:3]
	v_mov_b64_e32 v[42:43], v[6:7]
	s_cmp_eq_u32 s67, 1
	s_cselect_b64 s[4:5], -1, 0
	s_xor_b64 s[6:7], s[44:45], -1
	s_or_b64 s[4:5], s[6:7], s[4:5]
	s_and_b64 vcc, exec, s[4:5]
	s_cbranch_vccnz .LBB0_361
	global_store_dwordx2 v[114:115], v[108:109], off
	global_store_dwordx2 v[114:115], v[110:111], off offset:32
	global_store_dwordx2 v[114:115], v[112:113], off offset:64
	global_store_dwordx2 v[114:115], v[116:117], off offset:96

; #define LAS __attribute__((address_space(3)))
; __device__ __forceinline__ void ph_na_mfma(const Args& a, const Frame& F, int l) {
;     ...
;             if (it + j + 1 < i1) {
;                 int s0n, Rn, hn, rn; NA_ITEM(it + j + 1, s0n, Rn, hn, rn);
;                 if (half == 0 && j + 1 < m) { const int rsn = min(max(rn - 4, 0), Rn - 8); if (rsn > rs) { NA_ROW_DMA(ZK, rsn + 7, KR + ((rsn + 7) % 9) * 8192); NA_ROW_DMA(ZV, rsn + 7, VR + ((rsn + 7) % 9) * 8192); } }
;                 const bf16* qp = Z + ((size_t)hn * NTOK + (s0n + rn * 64 + c)) * 64 + 8 * g; qn0 = *(const pg8::bf16x8*)qp; qn1 = *(const pg8::bf16x8*)(qp + 32);
;             }
;             const int tokrow0 = s0 + r * 64;
;             f32x4 sc[4][2];
;             pg8::bf16x8 kf[4][2][2];
; #pragma unroll
;             for (int kk = 0; kk < 4; ++kk) { const int row = rs + 4 * half + kk; const LAS unsigned char* kb = L + KR + (row % 9) * 8192;
; #pragma unroll
;                 for (int blk = 0; blk < 2; ++blk) { const int col = kc0 + 8 * (q >> 2) + 4 * blk + (q & 3); const int sw = NA_SWZ(col);
;                     kf[kk][blk][0] = *(const LAS pg8::bf16x8*)(kb + col * 128 + ((g ^ sw) * 16)); kf[kk][blk][1] = *(const LAS pg8::bf16x8*)(kb + col * 128 + (((4 + g) ^ sw) * 16)); } }
;             const bool interior = (rs == r - 4);
;             __builtin_amdgcn_sched_barrier(0);
; #pragma unroll
;             for (int kk = 0; kk < 4; ++kk)
; #pragma unroll
;                 for (int blk = 0; blk < 2; ++blk) { f32x4 ini = (f32x4){0.f, 0.f, 0.f, 0.f};
;                     if (interior) ini = (f32x4){ti[kk][blk][0], ti[kk][blk][1], ti[kk][blk][2], ti[kk][blk][3]};
;                     sc[kk][blk] = __builtin_amdgcn_mfma_f32_16x16x32_bf16(kf[kk][blk][0], qf0, ini, 0, 0, 0); }
; #pragma unroll
;             for (int kk = 0; kk < 4; ++kk)
; #pragma unroll
;                 for (int blk = 0; blk < 2; ++blk) sc[kk][blk] = __builtin_amdgcn_mfma_f32_16x16x32_bf16(kf[kk][blk][1], qf1, sc[kk][blk], 0, 0, 0);
;             __builtin_amdgcn_sched_barrier(0);
;             if (!interior) {
;                 const LAS float* bh = (const LAS float*)(L + BIAS) + (rs + 4 * half - r + 7) * 31;
; #pragma unroll
;                 for (int blk = 0; blk < 2; ++blk)
; #pragma unroll
.LBB0_368:
	v_lshl_or_b32 v2, s4, 6, v41
	s_and_b32 s5, s5, 15
	v_add_u32_e32 v2, s6, v2
	s_mul_i32 s82, s5, 0xa000
	v_ashrrev_i32_e32 v3, 31, v2
	v_lshl_add_u64 v[2:3], v[2:3], 0, s[82:83]
	v_lshlrev_b64 v[2:3], 7, v[2:3]
	v_lshl_add_u64 v[6:7], v[90:91], 0, v[2:3]
	s_cmp_lg_u64 s[44:45], 0
	s_cbranch_scc0 .Lna_nopf_a
	s_mov_b32 s101, 0
	s_mov_b32 s100, 0x500a000
	v_lshl_add_u64 v[184:185], v[6:7], 0, s[100:101]
	s_mov_b32 s100, 0xa00a000
	v_lshl_add_u64 v[186:187], v[6:7], 0, s[100:101]
	s_mov_b32 s100, 0x4000
	v_lshl_add_u64 v[194:195], v[6:7], 0, s[100:101]
.Lna_nopf_a:
	global_load_dwordx4 v[2:5], v[6:7], off
	s_nop 0
	global_load_dwordx4 v[6:9], v[6:7], off offset:64
	s_cmp_lg_u64 s[44:45], 0
	s_cbranch_scc0 .Lna_nopf_b
	global_load_dword v193, v[184:185], off
	global_load_dword v193, v[186:187], off
	global_load_dword v193, v[194:195], off
.Lna_nopf_b:
.LBB0_369:
	s_add_i32 s4, s9, s33
	s_mul_hi_u32 s5, s4, 0x38e38e39
	s_lshr_b32 s5, s5, 1
	s_mul_i32 s5, s5, 9
	s_sub_i32 s5, s4, s5
	s_lshl_b32 s7, s5, 13
	s_add_i32 s5, s4, 1
	s_mul_hi_u32 s6, s5, 0x38e38e39
	s_lshr_b32 s6, s6, 1
	s_mul_i32 s6, s6, 9
	s_sub_i32 s5, s5, s6
	s_lshl_b32 s6, s5, 13
	s_add_i32 s5, s4, 2
	s_mul_hi_u32 s10, s5, 0x38e38e39
	s_lshr_b32 s10, s10, 1
	s_mul_i32 s10, s10, 9
	s_add_i32 s4, s4, 3
	s_sub_i32 s5, s5, s10
	s_mul_hi_u32 s10, s4, 0x38e38e39
	v_add_u32_e32 v50, s7, v155
	v_add_u32_e32 v66, s6, v155
	s_lshr_b32 s10, s10, 1
	v_add_u32_e32 v54, v50, v124
	v_add_u32_e32 v62, v50, v125
	v_add_u32_e32 v70, v66, v124
	v_add_u32_e32 v78, v66, v125
	s_lshl_b32 s5, s5, 13
	s_mul_i32 s10, s10, 9
	ds_read_b128 v[50:53], v54
	ds_read_b128 v[54:57], v54 offset:512
	ds_read_b128 v[58:61], v62
	ds_read_b128 v[62:65], v62 offset:512
	ds_read_b128 v[66:69], v70
	ds_read_b128 v[70:73], v70 offset:512
	ds_read_b128 v[74:77], v78
	ds_read_b128 v[82:85], v78 offset:512
	v_add_u32_e32 v78, s5, v155
	s_sub_i32 s4, s4, s10
	v_add_u32_e32 v86, v78, v124
	v_add_u32_e32 v121, v78, v125
	s_lshl_b32 s4, s4, 13
	ds_read_b128 v[78:81], v86
	ds_read_b128 v[86:89], v86 offset:512
	ds_read_b128 v[160:163], v121
	ds_read_b128 v[164:167], v121 offset:512
	v_add_u32_e32 v121, s4, v155
	v_add_u32_e32 v159, v121, v124
	v_add_u32_e32 v121, v121, v125
	ds_read_b128 v[168:171], v159
	ds_read_b128 v[172:175], v159 offset:512
	ds_read_b128 v[176:179], v121
	ds_read_b128 v[180:183], v121 offset:512
	s_cmp_eq_u32 s8, s9
	s_cselect_b64 vcc, -1, 0
	v_cndmask_b32_e32 v209, 0, v11, vcc
	v_cndmask_b32_e32 v208, 0, v12, vcc
	v_cndmask_b32_e32 v207, 0, v1, vcc
	v_cndmask_b32_e32 v206, 0, v10, vcc
	s_waitcnt lgkmcnt(14)
	s_nop 0
	v_mfma_f32_16x16x32_bf16 v[50:53], v[50:53], v[46:49], v[206:209]
	s_nop 2
	v_cndmask_b32_e32 v209, 0, v15, vcc
	v_cndmask_b32_e32 v208, 0, v16, vcc
	v_cndmask_b32_e32 v207, 0, v13, vcc
	v_cndmask_b32_e32 v206, 0, v14, vcc
	s_nop 1
	v_mfma_f32_16x16x32_bf16 v[54:57], v[54:57], v[46:49], v[206:209]
	s_nop 2
	v_cndmask_b32_e32 v209, 0, v19, vcc
	v_cndmask_b32_e32 v208, 0, v20, vcc
	v_cndmask_b32_e32 v207, 0, v17, vcc
	v_cndmask_b32_e32 v206, 0, v18, vcc
	s_waitcnt lgkmcnt(12)
	v_mfma_f32_16x16x32_bf16 v[54:57], v[62:65], v[42:45], v[54:57]
	s_waitcnt lgkmcnt(11)
	v_mfma_f32_16x16x32_bf16 v[66:69], v[66:69], v[46:49], v[206:209]
	s_nop 2
	v_cndmask_b32_e32 v209, 0, v23, vcc
	v_cndmask_b32_e32 v208, 0, v24, vcc
	v_cndmask_b32_e32 v207, 0, v21, vcc
	v_cndmask_b32_e32 v206, 0, v22, vcc
	s_waitcnt lgkmcnt(9)
	v_mfma_f32_16x16x32_bf16 v[74:77], v[74:77], v[42:45], v[66:69]
	v_mfma_f32_16x16x32_bf16 v[70:73], v[70:73], v[46:49], v[206:209]
	s_nop 2
	v_cndmask_b32_e32 v209, 0, v27, vcc
	v_cndmask_b32_e32 v208, 0, v28, vcc
	v_cndmask_b32_e32 v207, 0, v25, vcc
	v_cndmask_b32_e32 v206, 0, v26, vcc
	s_waitcnt lgkmcnt(7)
	s_nop 0
	v_mfma_f32_16x16x32_bf16 v[206:209], v[78:81], v[46:49], v[206:209]
	v_cndmask_b32_e32 v81, 0, v31, vcc
	v_cndmask_b32_e32 v80, 0, v32, vcc
	v_cndmask_b32_e32 v79, 0, v29, vcc
	v_cndmask_b32_e32 v78, 0, v30, vcc
	s_waitcnt lgkmcnt(6)
	s_nop 0
	v_mfma_f32_16x16x32_bf16 v[86:89], v[86:89], v[46:49], v[78:81]
	s_nop 2
	v_cndmask_b32_e32 v81, 0, v35, vcc
	v_cndmask_b32_e32 v80, 0, v36, vcc
	v_cndmask_b32_e32 v79, 0, v33, vcc
	v_cndmask_b32_e32 v78, 0, v34, vcc
	s_waitcnt lgkmcnt(3)
	s_nop 0
	v_mfma_f32_16x16x32_bf16 v[168:171], v[168:171], v[46:49], v[78:81]
	s_nop 2
	v_cndmask_b32_e32 v81, 0, v39, vcc
	v_cndmask_b32_e32 v80, 0, v40, vcc
	v_cndmask_b32_e32 v79, 0, v37, vcc
	v_cndmask_b32_e32 v78, 0, v38, vcc
	s_waitcnt lgkmcnt(2)
	s_nop 0
	v_mfma_f32_16x16x32_bf16 v[172:175], v[172:175], v[46:49], v[78:81]
	v_mfma_f32_16x16x32_bf16 v[78:81], v[58:61], v[42:45], v[50:53]
	v_mfma_f32_16x16x32_bf16 v[50:53], v[82:85], v[42:45], v[70:73]
	v_mfma_f32_16x16x32_bf16 v[70:73], v[160:163], v[42:45], v[206:209]
	v_mfma_f32_16x16x32_bf16 v[46:49], v[164:167], v[42:45], v[86:89]
	s_waitcnt lgkmcnt(1)
	v_mfma_f32_16x16x32_bf16 v[58:61], v[176:179], v[42:45], v[168:171]
	s_waitcnt lgkmcnt(0)
	v_mfma_f32_16x16x32_bf16 v[42:45], v[180:183], v[42:45], v[172:175]
	s_and_b64 vcc, exec, vcc
	s_cbranch_vccnz .LBB0_435
	s_max_i32 s8, s59, 0
	s_min_i32 s8, s8, s36
	s_add_i32 s8, s8, s66
	s_mulk_i32 s8, 0x7c
	s_add_i32 s8, s8, 0
	s_add_i32 s8, s8, 0x24000
	v_lshl_add_u32 v63, v127, 2, s8
	v_mov_b32_e32 v66, 0xff800000
	v_mov_b32_e32 v62, 0xff800000
	s_and_saveexec_b64 s[26:27], s[92:93]
	s_cbranch_execz .LBB0_372
	ds_read_b32 v62, v63 offset:868
	s_waitcnt lgkmcnt(0)
	v_fmamk_f32 v62, v62, 0x41000000, v78
